# v55 + up GEMM: leading half issues 13 of the next unit's 16 first-tile fragment ds_reads at the start of its epilogue (free registers, data already visible) and skips them in the unit header
# baseline (speedup 1.0000x reference)
.LBB0_176:
	s_andn2_b64 vcc, exec, s[44:45]
	s_mov_b32 s80, s20
	s_mov_b32 s81, s46
	s_mov_b64 s[60:61], s[50:51]
	s_mov_b64 s[62:63], s[48:49]
	s_cbranch_vccz .LBB0_186
	s_bitcmp1_b32 s18, 0
	s_cbranch_scc1 .Lmy_up_h2
.LBB0_177:
	v_add_u32_e32 v142, 0x14000, v145
	ds_read_b128 v[184:187], v142
	ds_read_b128 v[188:191], v142 offset:1024
	ds_read_b128 v[192:195], v142 offset:2048
	ds_read_b128 v[196:199], v142 offset:3072
	v_add_u32_e32 v142, 0x10000, v145
	ds_read_b128 v[180:183], v142 offset:3072
	ds_read_b128 v[210:213], v148
	ds_read_b128 v[214:217], v148 offset:1024
	ds_read_b128 v[218:221], v148 offset:2048
	ds_read_b128 v[224:227], v148 offset:3072
	ds_read_b128 v[228:231], v148 offset:4096
	ds_read_b128 v[232:235], v148 offset:5120
	ds_read_b128 v[236:239], v148 offset:6144
	ds_read_b128 v[240:243], v148 offset:7168
.Lmy_up_h2:
	s_add_i32 s86, 0, 0x10000
	v_add_u32_e32 v142, s86, v145
	s_add_i32 s92, 0, 0x14000
	ds_read_b128 v[138:141], v142
	ds_read_b128 v[172:175], v142 offset:1024
	ds_read_b128 v[176:179], v142 offset:2048
	s_add_i32 s79, s79, 1
	s_mul_i32 s21, s79, s33
	s_mul_hi_u32 s44, s79, s94
	s_add_i32 s44, s44, s21
	s_mul_i32 s21, s79, s94
	s_add_u32 s48, s21, s2
	s_addc_u32 s49, s44, s3
	v_cmp_gt_i64_e32 vcc, s[48:49], v[158:159]
	v_cmp_lt_i64_e64 s[44:45], s[48:49], v[160:161]
	s_cbranch_vccnz .LBB0_179
	s_ashr_i32 s20, s48, 31
	s_lshr_b32 s20, s20, 29
	s_add_i32 s20, s48, s20
	s_ashr_i32 s21, s20, 3
	s_and_b32 s20, s20, -8
	s_sub_i32 s20, s48, s20
	s_cmp_lt_i32 s20, 0
	s_cselect_b32 s46, s36, 0x160
	s_mul_i32 s20, s20, s46
	s_add_i32 s20, s20, s21
	s_mul_hi_i32 s21, s20, 0x2e8ba2e9
	s_lshr_b32 s46, s21, 31
	s_ashr_i32 s21, s21, 5
	s_add_i32 s21, s21, s46
	s_lshl_b32 s46, s21, 3
	s_sub_i32 s47, 0x80, s46
	s_min_i32 s47, s47, 8
	s_mulk_i32 s21, 0xb0
	s_sub_i32 s21, s20, s21
	s_lshr_b32 s20, s21, 3
	s_and_b32 s21, s21, 7
	s_add_i32 s46, s46, s21

.LBB0_183:
	s_lshl_b32 s47, s81, 7
	s_and_b32 s47, s47, 0xc00
	v_add_u32_e32 v138, s47, v146
	ds_read2_b32 v[172:173], v138 offset1:16
	ds_read2_b32 v[142:143], v138 offset0:32 offset1:48
	ds_read2_b32 v[140:141], v138 offset0:128 offset1:144
	ds_read2_b32 v[138:139], v138 offset0:160 offset1:176
	v_pk_mul_f32 v[120:121], v[124:125], v[120:121]
	s_waitcnt lgkmcnt(0)
	s_bitcmp1_b32 s18, 0
	s_cbranch_scc0 .Lmy_up_e1
	v_add_u32_e32 v244, 0x14000, v145
	ds_read_b128 v[184:187], v244
	ds_read_b128 v[188:191], v244 offset:1024
	ds_read_b128 v[192:195], v244 offset:2048
	ds_read_b128 v[196:199], v244 offset:3072
	v_add_u32_e32 v245, 0x10000, v145
	ds_read_b128 v[180:183], v245 offset:3072
	ds_read_b128 v[210:213], v148
	ds_read_b128 v[214:217], v148 offset:1024
	ds_read_b128 v[218:221], v148 offset:2048
	ds_read_b128 v[224:227], v148 offset:3072
	ds_read_b128 v[228:231], v148 offset:4096
	ds_read_b128 v[232:235], v148 offset:5120
	ds_read_b128 v[236:239], v148 offset:6144
	ds_read_b128 v[240:243], v148 offset:7168
.Lmy_up_e1:
	v_mul_f32_e32 v174, 0xbfb8aa3b, v172
	v_pk_mul_f32 v[176:177], v[126:127], v[174:175] op_sel_hi:[1,0]
	v_pk_mul_f32 v[178:179], v[124:125], v[174:175] op_sel_hi:[1,0]
	v_exp_f32_e32 v176, v176
	v_exp_f32_e32 v177, v177
	v_exp_f32_e32 v178, v178
	v_exp_f32_e32 v179, v179
	v_mul_f32_e32 v172, v172, v172
	v_pk_add_f32 v[176:177], v[176:177], 1.0 op_sel_hi:[1,0]
	v_pk_mul_f32 v[122:123], v[126:127], v[122:123]
	v_rcp_f32_e32 v176, v176
	v_rcp_f32_e32 v177, v177
	v_pk_add_f32 v[178:179], v[178:179], 1.0 op_sel_hi:[1,0]
	s_lshl_b32 s21, s81, 8
	v_rcp_f32_e32 v178, v178
	v_pk_mul_f32 v[124:125], v[172:173], v[176:177] op_sel_hi:[0,1]
	v_pk_mul_f32 v[176:177], v[118:119], v[174:175] op_sel_hi:[1,0]
	v_rcp_f32_e32 v179, v179
	v_pk_mul_f32 v[174:175], v[116:117], v[174:175] op_sel_hi:[1,0]
	v_exp_f32_e32 v176, v176
	v_exp_f32_e32 v177, v177
	v_exp_f32_e32 v174, v174
	v_exp_f32_e32 v175, v175
	v_pk_mul_f32 v[126:127], v[172:173], v[178:179] op_sel_hi:[0,1]
	v_pk_mul_f32 v[122:123], v[122:123], v[124:125]
	v_pk_add_f32 v[124:125], v[176:177], 1.0 op_sel_hi:[1,0]
	v_pk_mul_f32 v[120:121], v[120:121], v[126:127]
	v_pk_add_f32 v[126:127], v[174:175], 1.0 op_sel_hi:[1,0]
	v_rcp_f32_e32 v124, v124
	v_rcp_f32_e32 v125, v125
	v_rcp_f32_e32 v126, v126
	v_rcp_f32_e32 v127, v127
	v_pk_mul_f32 v[114:115], v[118:119], v[114:115]
	v_pk_mul_f32 v[112:113], v[116:117], v[112:113]
	v_pk_mul_f32 v[116:117], v[172:173], v[124:125] op_sel_hi:[0,1]
	s_add_i32 s21, s21, s76
	v_pk_mul_f32 v[118:119], v[172:173], v[126:127] op_sel_hi:[0,1]
	v_pk_mul_f32 v[114:115], v[114:115], v[116:117]
	v_cvt_pk_bf16_f32 v116, v120, v121
	v_cvt_pk_bf16_f32 v117, v122, v123
	v_mul_f32_e32 v122, 0xbfb8aa3b, v173
	s_ashr_i32 s60, s21, 12
	v_pk_mul_f32 v[112:113], v[112:113], v[118:119]
	v_pk_mul_f32 v[124:125], v[110:111], v[122:123] op_sel_hi:[1,0]
	v_pk_mul_f32 v[126:127], v[108:109], v[122:123] op_sel_hi:[1,0]
	v_or_b32_e32 v149, s21, v144
	v_lshl_or_b32 v150, s80, 7, v147
	s_ashr_i32 s61, s60, 31
	v_cvt_pk_bf16_f32 v118, v112, v113
	v_mov_b64_e32 v[112:113], s[56:57]
	v_exp_f32_e32 v126, v126
	v_exp_f32_e32 v124, v124
	v_exp_f32_e32 v125, v125
	v_exp_f32_e32 v127, v127
	v_ashrrev_i32_e32 v151, 31, v150
	v_cvt_pk_bf16_f32 v119, v114, v115
	v_mad_i64_i32 v[114:115], s[62:63], v149, s24, v[112:113]
	s_lshl_b64 s[60:61], s[60:61], 22
	v_lshl_add_u64 v[120:121], v[114:115], 0, s[60:61]
	v_lshlrev_b64 v[114:115], 1, v[150:151]
	v_lshl_add_u64 v[120:121], v[120:121], 0, v[114:115]
	global_store_dwordx4 v[120:121], v[116:119], off
	v_pk_add_f32 v[120:121], v[126:127], 1.0 op_sel_hi:[1,0]
	v_pk_mul_f32 v[106:107], v[110:111], v[106:107]
	v_pk_add_f32 v[118:119], v[124:125], 1.0 op_sel_hi:[1,0]
	v_rcp_f32_e32 v120, v120
	v_rcp_f32_e32 v118, v118
	v_rcp_f32_e32 v119, v119
	v_rcp_f32_e32 v121, v121
	v_mul_f32_e32 v116, v173, v173
	v_pk_mul_f32 v[104:105], v[108:109], v[104:105]
	v_pk_mul_f32 v[108:109], v[116:117], v[118:119] op_sel_hi:[0,1]
	v_pk_mul_f32 v[110:111], v[116:117], v[120:121] op_sel_hi:[0,1]
	v_pk_mul_f32 v[118:119], v[102:103], v[122:123] op_sel_hi:[1,0]
	v_pk_mul_f32 v[120:121], v[100:101], v[122:123] op_sel_hi:[1,0]
	v_exp_f32_e32 v118, v118
	v_exp_f32_e32 v120, v120
	v_exp_f32_e32 v119, v119
	v_exp_f32_e32 v121, v121
	v_pk_mul_f32 v[106:107], v[106:107], v[108:109]
	v_pk_mul_f32 v[104:105], v[104:105], v[110:111]
	v_pk_add_f32 v[108:109], v[118:119], 1.0 op_sel_hi:[1,0]
	v_pk_add_f32 v[110:111], v[120:121], 1.0 op_sel_hi:[1,0]
	v_rcp_f32_e32 v108, v108
	v_rcp_f32_e32 v110, v110
	v_rcp_f32_e32 v109, v109
	v_rcp_f32_e32 v111, v111
	v_pk_mul_f32 v[98:99], v[102:103], v[98:99]
	v_pk_mul_f32 v[96:97], v[100:101], v[96:97]
	v_pk_mul_f32 v[100:101], v[116:117], v[108:109] op_sel_hi:[0,1]
	v_pk_mul_f32 v[102:103], v[116:117], v[110:111] op_sel_hi:[0,1]
	v_pk_mul_f32 v[100:101], v[98:99], v[100:101]
	v_pk_mul_f32 v[98:99], v[96:97], v[102:103]
	v_or_b32_e32 v102, 16, v149
	v_cvt_pk_bf16_f32 v96, v104, v105
	v_cvt_pk_bf16_f32 v97, v106, v107
	v_cvt_pk_bf16_f32 v98, v98, v99
	v_cvt_pk_bf16_f32 v99, v100, v101
	v_mad_i64_i32 v[100:101], s[62:63], v102, s24, v[112:113]
	v_mul_f32_e32 v102, 0xbfb8aa3b, v142
	v_pk_mul_f32 v[104:105], v[94:95], v[102:103] op_sel_hi:[1,0]
	v_pk_mul_f32 v[106:107], v[92:93], v[102:103] op_sel_hi:[1,0]
	v_exp_f32_e32 v104, v104
	v_exp_f32_e32 v106, v106
	v_exp_f32_e32 v105, v105
	v_exp_f32_e32 v107, v107
	v_lshl_add_u64 v[100:101], v[100:101], 0, s[60:61]
	v_lshl_add_u64 v[100:101], v[100:101], 0, v[114:115]
	global_store_dwordx4 v[100:101], v[96:99], off
	v_pk_add_f32 v[100:101], v[106:107], 1.0 op_sel_hi:[1,0]
	v_pk_mul_f32 v[90:91], v[94:95], v[90:91]
	v_pk_add_f32 v[98:99], v[104:105], 1.0 op_sel_hi:[1,0]
	v_rcp_f32_e32 v100, v100
	v_rcp_f32_e32 v98, v98
	v_rcp_f32_e32 v99, v99
	v_rcp_f32_e32 v101, v101
	v_mul_f32_e32 v96, v142, v142
	v_pk_mul_f32 v[88:89], v[92:93], v[88:89]
	v_pk_mul_f32 v[92:93], v[96:97], v[98:99] op_sel_hi:[0,1]
	v_pk_mul_f32 v[94:95], v[96:97], v[100:101] op_sel_hi:[0,1]
	v_pk_mul_f32 v[98:99], v[86:87], v[102:103] op_sel_hi:[1,0]
	v_pk_mul_f32 v[100:101], v[84:85], v[102:103] op_sel_hi:[1,0]
	v_exp_f32_e32 v98, v98
	v_exp_f32_e32 v100, v100
	v_exp_f32_e32 v99, v99
	v_exp_f32_e32 v101, v101
	v_pk_mul_f32 v[90:91], v[90:91], v[92:93]
	v_pk_mul_f32 v[88:89], v[88:89], v[94:95]
	v_pk_add_f32 v[92:93], v[98:99], 1.0 op_sel_hi:[1,0]
	v_pk_add_f32 v[94:95], v[100:101], 1.0 op_sel_hi:[1,0]
	v_rcp_f32_e32 v92, v92
	v_rcp_f32_e32 v94, v94
	v_rcp_f32_e32 v93, v93
	v_rcp_f32_e32 v95, v95
	v_pk_mul_f32 v[82:83], v[86:87], v[82:83]
	v_pk_mul_f32 v[80:81], v[84:85], v[80:81]
	v_pk_mul_f32 v[84:85], v[96:97], v[92:93] op_sel_hi:[0,1]
	v_pk_mul_f32 v[86:87], v[96:97], v[94:95] op_sel_hi:[0,1]
	v_pk_mul_f32 v[84:85], v[82:83], v[84:85]
	v_pk_mul_f32 v[82:83], v[80:81], v[86:87]
	v_or_b32_e32 v86, 32, v149
	v_cvt_pk_bf16_f32 v80, v88, v89
	v_cvt_pk_bf16_f32 v81, v90, v91
	v_cvt_pk_bf16_f32 v82, v82, v83
	v_cvt_pk_bf16_f32 v83, v84, v85
	v_mad_i64_i32 v[84:85], s[62:63], v86, s24, v[112:113]
	v_mul_f32_e32 v86, 0xbfb8aa3b, v143
	v_pk_mul_f32 v[88:89], v[78:79], v[86:87] op_sel_hi:[1,0]
	v_pk_mul_f32 v[90:91], v[76:77], v[86:87] op_sel_hi:[1,0]
	v_exp_f32_e32 v88, v88
	v_exp_f32_e32 v90, v90
	v_exp_f32_e32 v89, v89
	v_exp_f32_e32 v91, v91
	v_lshl_add_u64 v[84:85], v[84:85], 0, s[60:61]
	v_lshl_add_u64 v[84:85], v[84:85], 0, v[114:115]
	global_store_dwordx4 v[84:85], v[80:83], off
	v_pk_add_f32 v[84:85], v[90:91], 1.0 op_sel_hi:[1,0]
	v_pk_mul_f32 v[74:75], v[78:79], v[74:75]
	v_pk_add_f32 v[82:83], v[88:89], 1.0 op_sel_hi:[1,0]
	v_rcp_f32_e32 v84, v84
	v_rcp_f32_e32 v82, v82
	v_rcp_f32_e32 v83, v83
	v_rcp_f32_e32 v85, v85
	v_mul_f32_e32 v80, v143, v143
	v_pk_mul_f32 v[72:73], v[76:77], v[72:73]
	v_pk_mul_f32 v[76:77], v[80:81], v[82:83] op_sel_hi:[0,1]
	v_pk_mul_f32 v[78:79], v[80:81], v[84:85] op_sel_hi:[0,1]
	v_pk_mul_f32 v[82:83], v[70:71], v[86:87] op_sel_hi:[1,0]
	v_pk_mul_f32 v[84:85], v[68:69], v[86:87] op_sel_hi:[1,0]
	v_exp_f32_e32 v82, v82
	v_exp_f32_e32 v84, v84
	v_exp_f32_e32 v83, v83
	v_exp_f32_e32 v85, v85
	v_pk_mul_f32 v[74:75], v[74:75], v[76:77]
	v_pk_mul_f32 v[72:73], v[72:73], v[78:79]
	v_pk_add_f32 v[76:77], v[82:83], 1.0 op_sel_hi:[1,0]
	v_pk_add_f32 v[78:79], v[84:85], 1.0 op_sel_hi:[1,0]
	v_rcp_f32_e32 v76, v76
	v_rcp_f32_e32 v78, v78
	v_rcp_f32_e32 v77, v77
	v_rcp_f32_e32 v79, v79
	v_pk_mul_f32 v[66:67], v[70:71], v[66:67]
	v_pk_mul_f32 v[64:65], v[68:69], v[64:65]
	v_pk_mul_f32 v[68:69], v[80:81], v[76:77] op_sel_hi:[0,1]
	v_pk_mul_f32 v[70:71], v[80:81], v[78:79] op_sel_hi:[0,1]
	v_pk_mul_f32 v[68:69], v[66:67], v[68:69]
	v_pk_mul_f32 v[66:67], v[64:65], v[70:71]
	v_or_b32_e32 v70, 48, v149
	v_cvt_pk_bf16_f32 v64, v72, v73
	v_cvt_pk_bf16_f32 v65, v74, v75
	v_cvt_pk_bf16_f32 v66, v66, v67
	v_cvt_pk_bf16_f32 v67, v68, v69
	v_mad_i64_i32 v[68:69], s[62:63], v70, s24, v[112:113]
	v_lshl_add_u64 v[68:69], v[68:69], 0, s[60:61]
	v_lshl_add_u64 v[68:69], v[68:69], 0, v[114:115]
	global_store_dwordx4 v[68:69], v[64:67], off
	v_add_u32_e32 v73, 0x80, v149
	v_mul_f32_e32 v72, v140, v140
	v_mul_f32_e32 v66, 0xbfb8aa3b, v140
	v_pk_mul_f32 v[68:69], v[62:63], v[66:67] op_sel_hi:[1,0]
	v_pk_mul_f32 v[70:71], v[60:61], v[66:67] op_sel_hi:[1,0]
	v_exp_f32_e32 v68, v68
	v_exp_f32_e32 v69, v69
	v_exp_f32_e32 v70, v70
	v_exp_f32_e32 v71, v71
	v_pk_mul_f32 v[56:57], v[60:61], v[56:57]
	v_pk_add_f32 v[68:69], v[68:69], 1.0 op_sel_hi:[1,0]
	v_pk_mul_f32 v[58:59], v[62:63], v[58:59]
	v_rcp_f32_e32 v68, v68
	v_rcp_f32_e32 v69, v69
	v_pk_add_f32 v[70:71], v[70:71], 1.0 op_sel_hi:[1,0]
	v_pk_mul_f32 v[50:51], v[54:55], v[50:51]
	v_rcp_f32_e32 v70, v70
	v_pk_mul_f32 v[60:61], v[72:73], v[68:69] op_sel_hi:[0,1]
	v_pk_mul_f32 v[68:69], v[54:55], v[66:67] op_sel_hi:[1,0]
	v_rcp_f32_e32 v71, v71
	v_pk_mul_f32 v[66:67], v[52:53], v[66:67] op_sel_hi:[1,0]
	v_exp_f32_e32 v68, v68
	v_exp_f32_e32 v69, v69
	v_exp_f32_e32 v66, v66
	v_exp_f32_e32 v67, v67
	v_pk_mul_f32 v[62:63], v[72:73], v[70:71] op_sel_hi:[0,1]
	v_pk_mul_f32 v[58:59], v[58:59], v[60:61]
	v_pk_add_f32 v[60:61], v[68:69], 1.0 op_sel_hi:[1,0]
	v_pk_mul_f32 v[56:57], v[56:57], v[62:63]
	v_pk_add_f32 v[62:63], v[66:67], 1.0 op_sel_hi:[1,0]
	v_rcp_f32_e32 v60, v60
	v_rcp_f32_e32 v61, v61
	v_rcp_f32_e32 v62, v62
	v_rcp_f32_e32 v63, v63
	v_pk_mul_f32 v[48:49], v[52:53], v[48:49]
	v_pk_mul_f32 v[52:53], v[72:73], v[60:61] op_sel_hi:[0,1]
	v_pk_mul_f32 v[60:61], v[50:51], v[52:53]
	v_pk_mul_f32 v[54:55], v[72:73], v[62:63] op_sel_hi:[0,1]
	v_cvt_pk_bf16_f32 v50, v56, v57
	v_mul_f32_e32 v56, 0xbfb8aa3b, v141
	v_ashrrev_i32_e32 v64, 12, v73
	v_pk_mul_f32 v[48:49], v[48:49], v[54:55]
	v_cvt_pk_bf16_f32 v51, v58, v59
	v_pk_mul_f32 v[58:59], v[46:47], v[56:57] op_sel_hi:[1,0]
	v_cvt_pk_bf16_f32 v52, v48, v49
	v_cvt_pk_bf16_f32 v53, v60, v61
	v_pk_mul_f32 v[60:61], v[44:45], v[56:57] op_sel_hi:[1,0]
	v_ashrrev_i32_e32 v65, 31, v64
	v_exp_f32_e32 v60, v60
	v_exp_f32_e32 v58, v58
	v_exp_f32_e32 v59, v59
	v_exp_f32_e32 v61, v61
	v_mad_i64_i32 v[54:55], s[60:61], v73, s24, v[112:113]
	v_lshlrev_b64 v[48:49], 22, v[64:65]
	v_lshl_add_u64 v[54:55], v[54:55], 0, v[48:49]
	v_lshl_add_u64 v[54:55], v[54:55], 0, v[114:115]
	global_store_dwordx4 v[54:55], v[50:53], off
	v_pk_add_f32 v[54:55], v[60:61], 1.0 op_sel_hi:[1,0]
	v_pk_mul_f32 v[42:43], v[46:47], v[42:43]
	v_pk_add_f32 v[52:53], v[58:59], 1.0 op_sel_hi:[1,0]
	v_rcp_f32_e32 v54, v54
	v_rcp_f32_e32 v52, v52
	v_rcp_f32_e32 v53, v53
	v_rcp_f32_e32 v55, v55
	v_mul_f32_e32 v50, v141, v141
	v_pk_mul_f32 v[40:41], v[44:45], v[40:41]
	v_pk_mul_f32 v[44:45], v[50:51], v[52:53] op_sel_hi:[0,1]
	v_pk_mul_f32 v[46:47], v[50:51], v[54:55] op_sel_hi:[0,1]
	v_pk_mul_f32 v[52:53], v[38:39], v[56:57] op_sel_hi:[1,0]
	v_pk_mul_f32 v[54:55], v[36:37], v[56:57] op_sel_hi:[1,0]
	v_exp_f32_e32 v52, v52
	v_exp_f32_e32 v54, v54
	v_exp_f32_e32 v53, v53
	v_exp_f32_e32 v55, v55
	v_pk_mul_f32 v[42:43], v[42:43], v[44:45]
	v_pk_mul_f32 v[40:41], v[40:41], v[46:47]
	v_pk_add_f32 v[44:45], v[52:53], 1.0 op_sel_hi:[1,0]
	v_pk_add_f32 v[46:47], v[54:55], 1.0 op_sel_hi:[1,0]
	v_rcp_f32_e32 v44, v44
	v_rcp_f32_e32 v46, v46
	v_rcp_f32_e32 v45, v45
	v_rcp_f32_e32 v47, v47
	v_pk_mul_f32 v[34:35], v[38:39], v[34:35]
	v_pk_mul_f32 v[32:33], v[36:37], v[32:33]
	v_pk_mul_f32 v[36:37], v[50:51], v[44:45] op_sel_hi:[0,1]
	v_pk_mul_f32 v[38:39], v[50:51], v[46:47] op_sel_hi:[0,1]
	v_pk_mul_f32 v[36:37], v[34:35], v[36:37]
	v_pk_mul_f32 v[34:35], v[32:33], v[38:39]
	v_add_u32_e32 v38, 0x90, v149
	v_cvt_pk_bf16_f32 v32, v40, v41
	v_cvt_pk_bf16_f32 v33, v42, v43
	v_cvt_pk_bf16_f32 v34, v34, v35
	v_cvt_pk_bf16_f32 v35, v36, v37
	v_mad_i64_i32 v[36:37], s[60:61], v38, s24, v[112:113]
	v_mul_f32_e32 v38, 0xbfb8aa3b, v138
	v_pk_mul_f32 v[40:41], v[30:31], v[38:39] op_sel_hi:[1,0]
	v_pk_mul_f32 v[42:43], v[28:29], v[38:39] op_sel_hi:[1,0]
	v_exp_f32_e32 v40, v40
	v_exp_f32_e32 v42, v42
	v_exp_f32_e32 v41, v41
	v_exp_f32_e32 v43, v43
	v_lshl_add_u64 v[36:37], v[36:37], 0, v[48:49]
	v_lshl_add_u64 v[36:37], v[36:37], 0, v[114:115]
	global_store_dwordx4 v[36:37], v[32:35], off
	v_pk_add_f32 v[36:37], v[42:43], 1.0 op_sel_hi:[1,0]
	v_pk_mul_f32 v[26:27], v[30:31], v[26:27]
	v_pk_add_f32 v[34:35], v[40:41], 1.0 op_sel_hi:[1,0]
	v_rcp_f32_e32 v36, v36
	v_rcp_f32_e32 v34, v34
	v_rcp_f32_e32 v35, v35
	v_rcp_f32_e32 v37, v37
	v_mul_f32_e32 v32, v138, v138
	v_pk_mul_f32 v[24:25], v[28:29], v[24:25]
	v_pk_mul_f32 v[28:29], v[32:33], v[34:35] op_sel_hi:[0,1]
	v_pk_mul_f32 v[30:31], v[32:33], v[36:37] op_sel_hi:[0,1]
	v_pk_mul_f32 v[34:35], v[22:23], v[38:39] op_sel_hi:[1,0]
	v_pk_mul_f32 v[36:37], v[20:21], v[38:39] op_sel_hi:[1,0]
	v_exp_f32_e32 v34, v34
	v_exp_f32_e32 v36, v36
	v_exp_f32_e32 v35, v35
	v_exp_f32_e32 v37, v37
	v_pk_mul_f32 v[26:27], v[26:27], v[28:29]
	v_pk_mul_f32 v[24:25], v[24:25], v[30:31]
	v_pk_add_f32 v[28:29], v[34:35], 1.0 op_sel_hi:[1,0]
	v_pk_add_f32 v[30:31], v[36:37], 1.0 op_sel_hi:[1,0]
	v_rcp_f32_e32 v28, v28
	v_rcp_f32_e32 v30, v30
	v_rcp_f32_e32 v29, v29
	v_rcp_f32_e32 v31, v31
	v_pk_mul_f32 v[18:19], v[22:23], v[18:19]
	v_pk_mul_f32 v[16:17], v[20:21], v[16:17]
	v_pk_mul_f32 v[20:21], v[32:33], v[28:29] op_sel_hi:[0,1]
	v_pk_mul_f32 v[22:23], v[32:33], v[30:31] op_sel_hi:[0,1]
	v_pk_mul_f32 v[20:21], v[18:19], v[20:21]
	v_pk_mul_f32 v[18:19], v[16:17], v[22:23]
	v_add_u32_e32 v22, 0xa0, v149
	v_cvt_pk_bf16_f32 v16, v24, v25
	v_cvt_pk_bf16_f32 v17, v26, v27
	v_cvt_pk_bf16_f32 v18, v18, v19
	v_cvt_pk_bf16_f32 v19, v20, v21
	v_mad_i64_i32 v[20:21], s[60:61], v22, s24, v[112:113]
	v_mul_f32_e32 v22, 0xbfb8aa3b, v139
	v_pk_mul_f32 v[24:25], v[14:15], v[22:23] op_sel_hi:[1,0]
	v_pk_mul_f32 v[26:27], v[12:13], v[22:23] op_sel_hi:[1,0]
	v_exp_f32_e32 v24, v24
	v_exp_f32_e32 v26, v26
	v_exp_f32_e32 v25, v25
	v_exp_f32_e32 v27, v27
	v_lshl_add_u64 v[20:21], v[20:21], 0, v[48:49]
	v_lshl_add_u64 v[20:21], v[20:21], 0, v[114:115]
	global_store_dwordx4 v[20:21], v[16:19], off
	v_pk_add_f32 v[20:21], v[26:27], 1.0 op_sel_hi:[1,0]
	v_pk_mul_f32 v[10:11], v[14:15], v[10:11]
	v_pk_add_f32 v[18:19], v[24:25], 1.0 op_sel_hi:[1,0]
	v_rcp_f32_e32 v20, v20
	v_rcp_f32_e32 v18, v18
	v_rcp_f32_e32 v19, v19
	v_rcp_f32_e32 v21, v21
	v_mul_f32_e32 v16, v139, v139
	v_pk_mul_f32 v[8:9], v[12:13], v[8:9]
	v_pk_mul_f32 v[12:13], v[16:17], v[18:19] op_sel_hi:[0,1]
	v_pk_mul_f32 v[14:15], v[16:17], v[20:21] op_sel_hi:[0,1]
	v_pk_mul_f32 v[18:19], v[6:7], v[22:23] op_sel_hi:[1,0]
	v_pk_mul_f32 v[20:21], v[4:5], v[22:23] op_sel_hi:[1,0]
	v_exp_f32_e32 v18, v18
	v_exp_f32_e32 v20, v20
	v_exp_f32_e32 v19, v19
	v_exp_f32_e32 v21, v21
	v_pk_mul_f32 v[10:11], v[10:11], v[12:13]
	v_pk_mul_f32 v[8:9], v[8:9], v[14:15]
	v_pk_add_f32 v[12:13], v[18:19], 1.0 op_sel_hi:[1,0]
	v_pk_add_f32 v[14:15], v[20:21], 1.0 op_sel_hi:[1,0]
	v_rcp_f32_e32 v12, v12
	v_rcp_f32_e32 v14, v14
	v_rcp_f32_e32 v13, v13
	v_rcp_f32_e32 v15, v15
	v_pk_mul_f32 v[2:3], v[6:7], v[2:3]
	v_pk_mul_f32 v[0:1], v[4:5], v[0:1]
	v_pk_mul_f32 v[4:5], v[16:17], v[12:13] op_sel_hi:[0,1]
	v_pk_mul_f32 v[6:7], v[16:17], v[14:15] op_sel_hi:[0,1]
	v_pk_mul_f32 v[4:5], v[2:3], v[4:5]
	v_pk_mul_f32 v[2:3], v[0:1], v[6:7]
	v_add_u32_e32 v6, 0xb0, v149
	v_cvt_pk_bf16_f32 v0, v8, v9
	v_cvt_pk_bf16_f32 v1, v10, v11
	v_cvt_pk_bf16_f32 v2, v2, v3
	v_cvt_pk_bf16_f32 v3, v4, v5
	v_mad_i64_i32 v[4:5], s[60:61], v6, s24, v[112:113]
	v_lshl_add_u64 v[4:5], v[4:5], 0, v[48:49]
	v_lshl_add_u64 v[4:5], v[4:5], 0, v[114:115]
	s_andn2_b64 vcc, exec, s[44:45]
	s_mov_b64 s[44:45], -1
	global_store_dwordx4 v[4:5], v[0:3], off
	s_cbranch_vccnz .LBB0_176
	s_andn2_b64 vcc, exec, s[16:17]
	s_cbranch_vccnz .LBB0_175
	s_barrier
	s_branch .LBB0_175
